# attention steps: the next block's LDS slot scalars and first ds_read addresses computed in front of the closing wait of the previous block, so each block starts with its ds_reads right after the barri
# baseline (speedup 1.0000x reference)
.LBB0_279:
	s_add_i32 s10, s44, 0xfffe8000
	s_and_b32 s10, s10, 0x10000
	s_xor_b32 s11, s10, 0x10000
	v_add_u32_e32 v209, s11, v224
	v_add_u32_e32 v112, v209, v223
	v_add_u32_e32 v208, s10, v234
	s_add_i32 s10, s93, s10
	s_branch .Latt_B_body
	s_nop 0
	s_nop 0
	s_nop 0

.Latt_A_body:
	ds_read_b128 v[96:99], v80 offset:32768
	ds_read_b128 v[184:187], v80 offset:40960
	v_add_u32_e32 v80, v237, v225
	ds_read_b128 v[180:183], v80 offset:32768
	ds_read_b128 v[176:179], v80 offset:40960
	v_add_u32_e32 v80, v236, v228
	ds_read_b128 v[172:175], v80 offset:16384
	ds_read_b128 v[168:171], v80 offset:20480
	ds_read_b128 v[164:167], v80 offset:24576
	ds_read_b128 v[160:163], v80 offset:28672
	v_mov_b32_e32 v80, v190
	s_nop 1
	v_permlane32_swap_b32_e32 v190, v80
	v_cmp_lt_f32_e32 vcc, s13, v190
	s_cbranch_vccz .LBB0_276
	v_max_f32_e32 v64, v190, v190
	v_max_f32_e32 v65, 0, v64
	v_exp_f32_e64 v80, -v65
	v_add_f32_e32 v229, v229, v65
	v_xor_b32_e32 v64, 0x80000000, v229
	v_sub_f32_e32 v127, v127, v65
	v_sub_f32_e32 v126, v126, v65
	v_sub_f32_e32 v125, v125, v65
	v_sub_f32_e32 v124, v124, v65
	v_sub_f32_e32 v123, v123, v65
	v_sub_f32_e32 v122, v122, v65
	v_sub_f32_e32 v121, v121, v65
	v_sub_f32_e32 v120, v120, v65
	v_sub_f32_e32 v119, v119, v65
	v_sub_f32_e32 v118, v118, v65
	v_sub_f32_e32 v117, v117, v65
	v_sub_f32_e32 v116, v116, v65
	v_sub_f32_e32 v115, v115, v65
	v_sub_f32_e32 v114, v114, v65
	v_sub_f32_e32 v113, v113, v65
	v_sub_f32_e32 v112, v112, v65
	v_sub_f32_e32 v143, v143, v65
	v_sub_f32_e32 v142, v142, v65
	v_sub_f32_e32 v141, v141, v65
	v_sub_f32_e32 v140, v140, v65
	v_sub_f32_e32 v139, v139, v65
	v_sub_f32_e32 v138, v138, v65
	v_sub_f32_e32 v137, v137, v65
	v_sub_f32_e32 v136, v136, v65
	v_sub_f32_e32 v135, v135, v65
	v_sub_f32_e32 v134, v134, v65
	v_sub_f32_e32 v133, v133, v65
	v_sub_f32_e32 v132, v132, v65
	v_sub_f32_e32 v131, v131, v65
	v_sub_f32_e32 v130, v130, v65
	v_sub_f32_e32 v129, v129, v65
	v_sub_f32_e32 v128, v128, v65
	v_mov_b32_e32 v65, v64
	v_mov_b32_e32 v66, v64
	v_mov_b32_e32 v67, v64
	v_mov_b32_e32 v68, v64
	v_mov_b32_e32 v69, v64
	v_mov_b32_e32 v70, v64
	v_mov_b32_e32 v71, v64
	v_mov_b32_e32 v72, v64
	v_mov_b32_e32 v73, v64
	v_mov_b32_e32 v74, v64
	v_mov_b32_e32 v75, v64
	v_mov_b32_e32 v76, v64
	v_mov_b32_e32 v77, v64
	v_mov_b32_e32 v78, v64
	v_mov_b32_e32 v79, v64
	v_pk_mul_f32 v[62:63], v[62:63], v[80:81] op_sel_hi:[1,0]
	v_pk_mul_f32 v[60:61], v[60:61], v[80:81] op_sel_hi:[1,0]
	v_pk_mul_f32 v[58:59], v[58:59], v[80:81] op_sel_hi:[1,0]
	v_pk_mul_f32 v[56:57], v[56:57], v[80:81] op_sel_hi:[1,0]
	v_pk_mul_f32 v[54:55], v[54:55], v[80:81] op_sel_hi:[1,0]
	v_pk_mul_f32 v[52:53], v[52:53], v[80:81] op_sel_hi:[1,0]
	v_pk_mul_f32 v[50:51], v[50:51], v[80:81] op_sel_hi:[1,0]
	v_pk_mul_f32 v[48:49], v[48:49], v[80:81] op_sel_hi:[1,0]
	v_pk_mul_f32 v[46:47], v[46:47], v[80:81] op_sel_hi:[1,0]
	v_pk_mul_f32 v[44:45], v[44:45], v[80:81] op_sel_hi:[1,0]
	v_pk_mul_f32 v[42:43], v[42:43], v[80:81] op_sel_hi:[1,0]
	v_pk_mul_f32 v[40:41], v[40:41], v[80:81] op_sel_hi:[1,0]
	v_pk_mul_f32 v[38:39], v[38:39], v[80:81] op_sel_hi:[1,0]
	v_pk_mul_f32 v[36:37], v[36:37], v[80:81] op_sel_hi:[1,0]
	v_pk_mul_f32 v[34:35], v[34:35], v[80:81] op_sel_hi:[1,0]
	v_pk_mul_f32 v[32:33], v[32:33], v[80:81] op_sel_hi:[1,0]
	v_pk_mul_f32 v[14:15], v[14:15], v[80:81] op_sel_hi:[1,0]
	v_pk_mul_f32 v[12:13], v[12:13], v[80:81] op_sel_hi:[1,0]
	v_pk_mul_f32 v[10:11], v[10:11], v[80:81] op_sel_hi:[1,0]
	v_pk_mul_f32 v[8:9], v[8:9], v[80:81] op_sel_hi:[1,0]
	v_pk_mul_f32 v[6:7], v[6:7], v[80:81] op_sel_hi:[1,0]
	v_pk_mul_f32 v[4:5], v[4:5], v[80:81] op_sel_hi:[1,0]
	v_pk_mul_f32 v[2:3], v[2:3], v[80:81] op_sel_hi:[1,0]
	v_pk_mul_f32 v[0:1], v[0:1], v[80:81] op_sel_hi:[1,0]
	v_pk_mul_f32 v[30:31], v[30:31], v[80:81] op_sel_hi:[1,0]
	v_pk_mul_f32 v[28:29], v[28:29], v[80:81] op_sel_hi:[1,0]
	v_pk_mul_f32 v[26:27], v[26:27], v[80:81] op_sel_hi:[1,0]
	v_pk_mul_f32 v[24:25], v[24:25], v[80:81] op_sel_hi:[1,0]
	v_pk_mul_f32 v[22:23], v[22:23], v[80:81] op_sel_hi:[1,0]
	v_pk_mul_f32 v[20:21], v[20:21], v[80:81] op_sel_hi:[1,0]
	v_pk_mul_f32 v[18:19], v[18:19], v[80:81] op_sel_hi:[1,0]
	v_pk_mul_f32 v[16:17], v[16:17], v[80:81] op_sel_hi:[1,0]
	v_pk_mul_f32 v[188:189], v[188:189], v[80:81] op_sel_hi:[1,0]

.Latt_dA3:
	v_mfma_f32_32x32x16_bf16 v[48:63], v[172:175], v[188:191], v[48:63]
	v_exp_f32_e32 v132, v132
	v_exp_f32_e32 v133, v133
	v_add_f32_e32 v172, v132, v237
	v_add_f32_e32 v173, v133, v219
	v_mfma_f32_32x32x16_bf16 v[32:47], v[168:171], v[188:191], v[32:47]
	v_exp_f32_e32 v134, v134
	v_exp_f32_e32 v135, v135
	v_add_f32_e32 v168, v134, v172
	v_add_f32_e32 v169, v135, v173
	v_mfma_f32_32x32x16_bf16 v[0:15], v[164:167], v[188:191], v[0:15]
	v_exp_f32_e32 v136, v136
	v_exp_f32_e32 v137, v137
	v_cvt_pk_bf16_f32 v164, v128, v129
	v_cvt_pk_bf16_f32 v165, v130, v131
	v_add_f32_e32 v166, v136, v168
	v_add_f32_e32 v167, v137, v169
	v_mfma_f32_32x32x16_bf16 v[16:31], v[160:163], v[188:191], v[16:31]
	v_exp_f32_e32 v138, v138
	v_exp_f32_e32 v139, v139
	v_add_f32_e32 v160, v138, v166
	v_add_f32_e32 v161, v139, v167
	v_cvt_pk_bf16_f32 v166, v132, v133
	v_cvt_pk_bf16_f32 v167, v134, v135
	v_exp_f32_e32 v140, v140
	v_exp_f32_e32 v141, v141
	s_waitcnt lgkmcnt(0)
	v_mfma_f32_32x32x16_bf16 v[48:63], v[238:241], v[176:179], v[48:63]
	v_add_u32_e32 v190, v236, v231
	v_add_f32_e32 v172, v140, v160
	v_add_f32_e32 v173, v141, v161
	ds_read_b128 v[160:163], v190 offset:16384
	ds_read_b128 v[168:171], v190 offset:20480
	v_exp_f32_e32 v142, v142
	v_exp_f32_e32 v143, v143
	v_mfma_f32_32x32x16_bf16 v[32:47], v[194:197], v[176:179], v[32:47]
	v_add_f32_e32 v189, v142, v172
	v_add_f32_e32 v188, v143, v173
	ds_read_b128 v[172:175], v190 offset:24576
	ds_read_b128 v[194:197], v190 offset:28672
	v_mfma_f32_32x32x16_bf16 v[0:15], v[184:187], v[176:179], v[0:15]
	v_cvt_pk_bf16_f32 v184, v136, v137
	v_cvt_pk_bf16_f32 v185, v138, v139
	v_mfma_f32_32x32x16_bf16 v[16:31], v[180:183], v[176:179], v[16:31]
	v_cvt_pk_bf16_f32 v186, v140, v141
	v_cvt_pk_bf16_f32 v187, v142, v143
	s_waitcnt lgkmcnt(0)
	v_mfma_f32_32x32x16_bf16 v[48:63], v[160:163], v[164:167], v[48:63]
	v_add_u32_e32 v180, v236, v232
	ds_read_b128 v[160:163], v180 offset:16384
	ds_read_b128 v[176:179], v180 offset:20480
	v_max_f32_e32 v190, v80, v96
	v_max3_f32 v191, v97, v82, v98
	v_mfma_f32_32x32x16_bf16 v[32:47], v[168:171], v[164:167], v[32:47]
	ds_read_b128 v[168:171], v180 offset:24576
	ds_read_b128 v[180:183], v180 offset:28672
	v_max3_f32 v190, v190, v81, v83
	v_max3_f32 v191, v191, v84, v100
	v_mfma_f32_32x32x16_bf16 v[0:15], v[172:175], v[164:167], v[0:15]
	v_max3_f32 v172, v190, v99, v85
	v_max3_f32 v173, v191, v86, v102
	v_mfma_f32_32x32x16_bf16 v[16:31], v[194:197], v[164:167], v[16:31]
	v_max3_f32 v164, v172, v101, v87
	v_max3_f32 v165, v173, v88, v104
	s_waitcnt lgkmcnt(0)
	v_mfma_f32_32x32x16_bf16 v[48:63], v[160:163], v[184:187], v[48:63]
	v_max3_f32 v160, v164, v103, v89
	v_max3_f32 v161, v165, v90, v106
	v_mfma_f32_32x32x16_bf16 v[32:47], v[176:179], v[184:187], v[32:47]
	v_max3_f32 v160, v160, v105, v91
	v_max3_f32 v161, v161, v92, v108
	v_mfma_f32_32x32x16_bf16 v[0:15], v[168:171], v[184:187], v[0:15]
	v_max3_f32 v160, v160, v107, v93
	v_max3_f32 v161, v161, v94, v110
	v_mfma_f32_32x32x16_bf16 v[16:31], v[180:183], v[184:187], v[16:31]
	v_max3_f32 v160, v160, v109, v95
	v_max3_f32 v190, v160, v111, v161
	s_mov_b64 s[80:81], -1
	s_and_b64 vcc, exec, s[38:39]
	s_cbranch_vccnz .LBB0_277
	s_add_i32 s10, s44, 0xfffe8000
	s_and_b32 s10, s10, 0x10000
	s_xor_b32 s11, s10, 0x10000
	v_add_u32_e32 v209, s11, v224
	v_add_u32_e32 v112, v209, v223
	v_add_u32_e32 v208, s10, v234
	s_add_i32 s10, s93, s10
	s_add_i32 s14, s96, 6
	s_cmp_le_u32 s14, s94
	s_cselect_b64 s[38:39], -1, 0
	s_cmp_ge_u32 s45, s95
	s_waitcnt vmcnt(4) lgkmcnt(0)
	s_barrier
	s_cbranch_scc1 .LBB0_268
.Latt_B_body:
	ds_read_b128 v[128:131], v112
	ds_read_b128 v[184:187], v112 offset:8192
	v_add_u32_e32 v112, v209, v225
	ds_read_b128 v[180:183], v112
	ds_read_b128 v[176:179], v112 offset:8192
	v_add_u32_e32 v112, v208, v228
	ds_read_b128 v[172:175], v112 offset:49152
	ds_read_b128 v[168:171], v112 offset:53248
	ds_read_b128 v[164:167], v112 offset:57344
	ds_read_b128 v[160:163], v112 offset:61440
	v_mov_b32_e32 v112, v190
	s_nop 1
	v_permlane32_swap_b32_e32 v190, v112
	v_cmp_lt_f32_e32 vcc, s13, v190
	s_cbranch_vccz .LBB0_281
	v_max_f32_e32 v64, v190, v190
	v_max_f32_e32 v65, 0, v64
	v_exp_f32_e64 v112, -v65
	v_add_f32_e32 v229, v229, v65
	v_xor_b32_e32 v64, 0x80000000, v229
	v_sub_f32_e32 v95, v95, v65
	v_sub_f32_e32 v94, v94, v65
	v_sub_f32_e32 v93, v93, v65
	v_sub_f32_e32 v92, v92, v65
	v_sub_f32_e32 v91, v91, v65
	v_sub_f32_e32 v90, v90, v65
	v_sub_f32_e32 v89, v89, v65
	v_sub_f32_e32 v88, v88, v65
	v_sub_f32_e32 v87, v87, v65
	v_sub_f32_e32 v86, v86, v65
	v_sub_f32_e32 v85, v85, v65
	v_sub_f32_e32 v84, v84, v65
	v_sub_f32_e32 v83, v83, v65
	v_sub_f32_e32 v82, v82, v65
	v_sub_f32_e32 v81, v81, v65
	v_sub_f32_e32 v80, v80, v65
	v_sub_f32_e32 v111, v111, v65
	v_sub_f32_e32 v110, v110, v65
	v_sub_f32_e32 v109, v109, v65
	v_sub_f32_e32 v108, v108, v65
	v_sub_f32_e32 v107, v107, v65
	v_sub_f32_e32 v106, v106, v65
	v_sub_f32_e32 v105, v105, v65
	v_sub_f32_e32 v104, v104, v65
	v_sub_f32_e32 v103, v103, v65
	v_sub_f32_e32 v102, v102, v65
	v_sub_f32_e32 v101, v101, v65
	v_sub_f32_e32 v100, v100, v65
	v_sub_f32_e32 v99, v99, v65
	v_sub_f32_e32 v98, v98, v65
	v_sub_f32_e32 v97, v97, v65
	v_sub_f32_e32 v96, v96, v65
	v_mov_b32_e32 v65, v64
	v_mov_b32_e32 v66, v64
	v_mov_b32_e32 v67, v64
	v_mov_b32_e32 v68, v64
	v_mov_b32_e32 v69, v64
	v_mov_b32_e32 v70, v64
	v_mov_b32_e32 v71, v64
	v_mov_b32_e32 v72, v64
	v_mov_b32_e32 v73, v64
	v_mov_b32_e32 v74, v64
	v_mov_b32_e32 v75, v64
	v_mov_b32_e32 v76, v64
	v_mov_b32_e32 v77, v64
	v_mov_b32_e32 v78, v64
	v_mov_b32_e32 v79, v64
	v_pk_mul_f32 v[62:63], v[62:63], v[112:113] op_sel_hi:[1,0]
	v_pk_mul_f32 v[60:61], v[60:61], v[112:113] op_sel_hi:[1,0]
	v_pk_mul_f32 v[58:59], v[58:59], v[112:113] op_sel_hi:[1,0]
	v_pk_mul_f32 v[56:57], v[56:57], v[112:113] op_sel_hi:[1,0]
	v_pk_mul_f32 v[54:55], v[54:55], v[112:113] op_sel_hi:[1,0]
	v_pk_mul_f32 v[52:53], v[52:53], v[112:113] op_sel_hi:[1,0]
	v_pk_mul_f32 v[50:51], v[50:51], v[112:113] op_sel_hi:[1,0]
	v_pk_mul_f32 v[48:49], v[48:49], v[112:113] op_sel_hi:[1,0]
	v_pk_mul_f32 v[46:47], v[46:47], v[112:113] op_sel_hi:[1,0]
	v_pk_mul_f32 v[44:45], v[44:45], v[112:113] op_sel_hi:[1,0]
	v_pk_mul_f32 v[42:43], v[42:43], v[112:113] op_sel_hi:[1,0]
	v_pk_mul_f32 v[40:41], v[40:41], v[112:113] op_sel_hi:[1,0]
	v_pk_mul_f32 v[38:39], v[38:39], v[112:113] op_sel_hi:[1,0]
	v_pk_mul_f32 v[36:37], v[36:37], v[112:113] op_sel_hi:[1,0]
	v_pk_mul_f32 v[34:35], v[34:35], v[112:113] op_sel_hi:[1,0]
	v_pk_mul_f32 v[32:33], v[32:33], v[112:113] op_sel_hi:[1,0]
	v_pk_mul_f32 v[14:15], v[14:15], v[112:113] op_sel_hi:[1,0]
	v_pk_mul_f32 v[12:13], v[12:13], v[112:113] op_sel_hi:[1,0]
	v_pk_mul_f32 v[10:11], v[10:11], v[112:113] op_sel_hi:[1,0]
	v_pk_mul_f32 v[8:9], v[8:9], v[112:113] op_sel_hi:[1,0]
	v_pk_mul_f32 v[6:7], v[6:7], v[112:113] op_sel_hi:[1,0]
	v_pk_mul_f32 v[4:5], v[4:5], v[112:113] op_sel_hi:[1,0]
	v_pk_mul_f32 v[2:3], v[2:3], v[112:113] op_sel_hi:[1,0]
	v_pk_mul_f32 v[0:1], v[0:1], v[112:113] op_sel_hi:[1,0]
	v_pk_mul_f32 v[30:31], v[30:31], v[112:113] op_sel_hi:[1,0]
	v_pk_mul_f32 v[28:29], v[28:29], v[112:113] op_sel_hi:[1,0]
	v_pk_mul_f32 v[26:27], v[26:27], v[112:113] op_sel_hi:[1,0]
	v_pk_mul_f32 v[24:25], v[24:25], v[112:113] op_sel_hi:[1,0]
	v_pk_mul_f32 v[22:23], v[22:23], v[112:113] op_sel_hi:[1,0]
	v_pk_mul_f32 v[20:21], v[20:21], v[112:113] op_sel_hi:[1,0]
	v_pk_mul_f32 v[18:19], v[18:19], v[112:113] op_sel_hi:[1,0]
	v_pk_mul_f32 v[16:17], v[16:17], v[112:113] op_sel_hi:[1,0]
	v_pk_mul_f32 v[188:189], v[188:189], v[112:113] op_sel_hi:[1,0]

; __device__ __forceinline__ void attn_unit2(LAS unsigned char* lds, const bf16_t* Q, const bf16_t* K, const bf16_t* VT, bf16_t* Y, const float* subg, float lam, float outscale, int b, int h, int qb, int wid0) {
;     ...
;     for (int t = 0; t < nta; t += 2) {
;         A2_STEP(sA, sB, nA, nB, t);
;         A2_STEP(nA, nB, sA, sB, t + 1);
;     }
.LBB0_282:
	s_add_i32 s44, s44, 0x10000
	s_cmp_ge_u32 s45, s94
	s_cbranch_scc1 .Latt_exit_pre
	s_add_i32 s10, s44, 0xfffe8000
	s_and_b32 s10, s10, 0x10000
	v_add_u32_e32 v237, s10, v222
	v_add_u32_e32 v80, v237, v223
	v_add_u32_e32 v236, s10, v233
	s_and_b32 s11, s44, 0x18000
	s_add_i32 s11, s93, s11
	s_mov_b32 s96, s45
	s_add_i32 s14, s96, 5
	s_cmp_ge_u32 s14, s22
	s_cselect_b64 s[38:39], -1, 0
	s_add_i32 s45, s96, 2
	s_cmp_gt_u32 s45, s95
	s_waitcnt vmcnt(4) lgkmcnt(0)
	s_barrier
	s_cbranch_scc0 .Latt_A_body
	s_branch .LBB0_263
